# compress stage 2: the eight w2 fragment loads issued together after stage 1 instead of one L2 round trip per MFMA
# speedup vs baseline: 1.0033x; 1.0033x over previous
; __device__ __forceinline__ unsigned cvt_pk_bf16(float lo, float hi) { const f32x2_t f = {lo, hi}; return __builtin_bit_cast(unsigned, __builtin_convertvector(f, bf16x2_t)); }
; __device__ __forceinline__ float bf_lo(unsigned u) { return __uint_as_float(u << 16); }
; __device__ __forceinline__ float bf_hi(unsigned u) { return __uint_as_float(u & 0xffff0000u); }
; __device__ __forceinline__ f32x4 mfma16(bf16x8 a, bf16x8 b, f32x4 c) { return __builtin_amdgcn_mfma_f32_16x16x32_bf16(a, b, c, 0, 0, 0); }
; __device__ __forceinline__ void compress_task(const Params& p, int task, char* smem) {
;     ...
; #pragma unroll 2
;     for (int kq = 0; kq < 16; ++kq) {
;         const int kk = w * 16 + kq, l = kk >> 1, d = (kk & 1) * 32 + fq * 8;
;         int tok = 16 * n + l; tok = tok < S ? tok : S - 1;
;         const u32x4 raw = *(const u32x4*)(src + (size_t)tok * LDA + d);
;         const float* pp = pos + l * 64 + d;
;         const f32x4 p0 = *(const f32x4*)pp, p1 = *(const f32x4*)(pp + 4);
;         u32x4 ap;
;         ap.x = cvt_pk_bf16(bf_lo(raw.x) + p0[0], bf_hi(raw.x) + p0[1]);
;         ap.y = cvt_pk_bf16(bf_lo(raw.y) + p0[2], bf_hi(raw.y) + p0[3]);
;         ap.z = cvt_pk_bf16(bf_lo(raw.z) + p1[0], bf_hi(raw.z) + p1[1]);
;         ap.w = cvt_pk_bf16(bf_lo(raw.w) + p1[2], bf_hi(raw.w) + p1[3]);
;         const bf16x8 a = __builtin_bit_cast(bf16x8, ap);
; #pragma unroll
;         for (int nt = 0; nt < 16; ++nt) {
;             const bf16x8 bw = *(const bf16x8*)(w1t + (size_t)(nt * 16 + fr) * 2048 + kk * 32 + fq * 8);
;             acc[nt] = mfma16(bw, a, acc[nt]);
;         }
;     }
.Lcp_loop:
	s_waitcnt vmcnt(16)
	v_lshlrev_b32_e32 v118, 16, v162
	v_and_b32_e32 v119, 0xffff0000, v162
	v_lshlrev_b32_e32 v120, 16, v163
	v_and_b32_e32 v121, 0xffff0000, v163
	v_lshlrev_b32_e32 v122, 16, v164
	v_and_b32_e32 v123, 0xffff0000, v164
	v_lshlrev_b32_e32 v124, 16, v165
	v_and_b32_e32 v125, 0xffff0000, v165
	v_pk_add_f32 v[118:119], v[166:167], v[118:119]
	v_pk_add_f32 v[120:121], v[168:169], v[120:121]
	v_pk_add_f32 v[122:123], v[170:171], v[122:123]
	v_pk_add_f32 v[124:125], v[172:173], v[124:125]
	v_cvt_pk_bf16_f32 v106, v118, v119
	v_cvt_pk_bf16_f32 v107, v120, v121
	v_cvt_pk_bf16_f32 v108, v122, v123
	v_cvt_pk_bf16_f32 v109, v124, v125
	v_lshlrev_b32_e32 v118, 16, v174
	v_and_b32_e32 v119, 0xffff0000, v174
	v_lshlrev_b32_e32 v120, 16, v175
	v_and_b32_e32 v121, 0xffff0000, v175
	v_lshlrev_b32_e32 v122, 16, v176
	v_and_b32_e32 v123, 0xffff0000, v176
	v_lshlrev_b32_e32 v124, 16, v177
	v_and_b32_e32 v125, 0xffff0000, v177
	v_pk_add_f32 v[118:119], v[246:247], v[118:119]
	v_pk_add_f32 v[120:121], v[248:249], v[120:121]
	v_pk_add_f32 v[122:123], v[250:251], v[122:123]
	v_pk_add_f32 v[124:125], v[252:253], v[124:125]
	v_cvt_pk_bf16_f32 v140, v118, v119
	v_cvt_pk_bf16_f32 v141, v120, v121
	v_cvt_pk_bf16_f32 v142, v122, v123
	v_cvt_pk_bf16_f32 v143, v124, v125
	v_add_u32_e32 v89, 1, v89
	v_add_u32_e32 v105, 1, v105
	v_lshl_add_u64 v[96:97], v[96:97], 0, s[14:15]
	v_lshl_add_u64 v[94:95], v[94:95], 0, s[14:15]
	v_lshl_add_u64 v[110:111], v[96:97], 0, v[86:87]
	v_min_u32_e32 v117, 0xfff, v89
	v_mul_u32_u24_e32 v117, 0x880, v117
	global_load_dwordx4 v[166:169], v[110:111], off
	global_load_dwordx4 v[170:173], v[110:111], off offset:16
	v_lshlrev_b32_e32 v64, 1, v117
	s_nop 0
	v_lshl_add_u64 v[126:127], v[90:91], 0, v[64:65]
	global_load_dwordx4 v[162:165], v[126:127], off
	v_lshl_add_u64 v[110:111], v[94:95], 0, v[86:87]
	v_min_u32_e32 v117, 0xfff, v105
	v_mul_u32_u24_e32 v117, 0x880, v117
	global_load_dwordx4 v[246:249], v[110:111], off offset:128
	global_load_dwordx4 v[250:253], v[110:111], off offset:144
	v_lshlrev_b32_e32 v64, 1, v117
	s_nop 0
	v_lshl_add_u64 v[126:127], v[90:91], 0, v[64:65]
	global_load_dwordx4 v[174:177], v[126:127], off offset:64
	s_waitcnt vmcnt(21)
	v_mfma_f32_16x16x32_bf16 v[60:63], v[180:183], v[106:109], v[60:63]
	s_add_u32 s100, s98, 0x80000
	s_addc_u32 s101, s99, 0
	global_load_dwordx4 v[180:183], v129, s[100:101]
	s_waitcnt vmcnt(21)
	v_mfma_f32_16x16x32_bf16 v[56:59], v[184:187], v[106:109], v[56:59]
	s_add_u32 s100, s98, 0x90000
	s_addc_u32 s101, s99, 0
	global_load_dwordx4 v[184:187], v129, s[100:101]
	s_waitcnt vmcnt(21)
	v_mfma_f32_16x16x32_bf16 v[60:63], v[188:191], v[140:143], v[60:63]
	s_add_u32 s100, s98, 0x80400
	s_addc_u32 s101, s99, 0
	global_load_dwordx4 v[188:191], v129, s[100:101]
	s_waitcnt vmcnt(21)
	v_mfma_f32_16x16x32_bf16 v[56:59], v[192:195], v[140:143], v[56:59]
	s_add_u32 s100, s98, 0x90400
	s_addc_u32 s101, s99, 0
	global_load_dwordx4 v[192:195], v129, s[100:101]
	s_waitcnt vmcnt(21)
	v_mfma_f32_16x16x32_bf16 v[52:55], v[196:199], v[106:109], v[52:55]
	s_add_u32 s100, s98, 0xa0000
	s_addc_u32 s101, s99, 0
	global_load_dwordx4 v[196:199], v129, s[100:101]
	s_waitcnt vmcnt(21)
	v_mfma_f32_16x16x32_bf16 v[48:51], v[200:203], v[106:109], v[48:51]
	s_add_u32 s100, s98, 0xb0000
	s_addc_u32 s101, s99, 0
	global_load_dwordx4 v[200:203], v129, s[100:101]
	s_waitcnt vmcnt(21)
	v_mfma_f32_16x16x32_bf16 v[52:55], v[204:207], v[140:143], v[52:55]
	s_add_u32 s100, s98, 0xa0400
	s_addc_u32 s101, s99, 0
	global_load_dwordx4 v[204:207], v129, s[100:101]
	s_waitcnt vmcnt(21)
	v_mfma_f32_16x16x32_bf16 v[48:51], v[208:211], v[140:143], v[48:51]
	s_add_u32 s100, s98, 0xb0400
	s_addc_u32 s101, s99, 0
	global_load_dwordx4 v[208:211], v129, s[100:101]
	s_waitcnt vmcnt(21)
	v_mfma_f32_16x16x32_bf16 v[44:47], v[212:215], v[106:109], v[44:47]
	s_add_u32 s100, s98, 0xc0000
	s_addc_u32 s101, s99, 0
	global_load_dwordx4 v[212:215], v129, s[100:101]
	s_waitcnt vmcnt(21)
	v_mfma_f32_16x16x32_bf16 v[40:43], v[216:219], v[106:109], v[40:43]
	s_add_u32 s100, s98, 0xd0000
	s_addc_u32 s101, s99, 0
	global_load_dwordx4 v[216:219], v129, s[100:101]
	s_waitcnt vmcnt(21)
	v_mfma_f32_16x16x32_bf16 v[44:47], v[220:223], v[140:143], v[44:47]
	s_add_u32 s100, s98, 0xc0400
	s_addc_u32 s101, s99, 0
	global_load_dwordx4 v[220:223], v129, s[100:101]
	s_waitcnt vmcnt(21)
	v_mfma_f32_16x16x32_bf16 v[40:43], v[224:227], v[140:143], v[40:43]
	s_add_u32 s100, s98, 0xd0400
	s_addc_u32 s101, s99, 0
	global_load_dwordx4 v[224:227], v129, s[100:101]
	s_waitcnt vmcnt(21)
	v_mfma_f32_16x16x32_bf16 v[36:39], v[228:231], v[106:109], v[36:39]
	s_add_u32 s100, s98, 0xe0000
	s_addc_u32 s101, s99, 0
	global_load_dwordx4 v[228:231], v129, s[100:101]
	s_waitcnt vmcnt(21)
	v_mfma_f32_16x16x32_bf16 v[32:35], v[232:235], v[106:109], v[32:35]
	s_add_u32 s100, s98, 0xf0000
	s_addc_u32 s101, s99, 0
	global_load_dwordx4 v[232:235], v129, s[100:101]
	s_waitcnt vmcnt(21)
	v_mfma_f32_16x16x32_bf16 v[36:39], v[236:239], v[140:143], v[36:39]
	s_add_u32 s100, s98, 0xe0400
	s_addc_u32 s101, s99, 0
	global_load_dwordx4 v[236:239], v129, s[100:101]
	s_waitcnt vmcnt(21)
	v_mfma_f32_16x16x32_bf16 v[32:35], v[240:243], v[140:143], v[32:35]
	s_add_u32 s100, s98, 0xf0400
	s_addc_u32 s101, s99, 0
	global_load_dwordx4 v[240:243], v129, s[100:101]
	s_add_u32 s98, s98, 0x800
	s_addc_u32 s99, s99, 0
	s_waitcnt vmcnt(15)
	v_mfma_f32_16x16x32_bf16 v[28:31], v[180:183], v[106:109], v[28:31]
	global_load_dwordx4 v[180:183], v129, s[98:99]
	s_waitcnt vmcnt(15)
	v_mfma_f32_16x16x32_bf16 v[24:27], v[184:187], v[106:109], v[24:27]
	s_add_u32 s100, s98, 0x10000
	s_addc_u32 s101, s99, 0
	global_load_dwordx4 v[184:187], v129, s[100:101]
	s_waitcnt vmcnt(15)
; __device__ __forceinline__ unsigned cvt_pk_bf16(float lo, float hi) { const f32x2_t f = {lo, hi}; return __builtin_bit_cast(unsigned, __builtin_convertvector(f, bf16x2_t)); }
; __device__ __forceinline__ float bf_lo(unsigned u) { return __uint_as_float(u << 16); }
; __device__ __forceinline__ float bf_hi(unsigned u) { return __uint_as_float(u & 0xffff0000u); }
; __device__ __forceinline__ f32x4 mfma16(bf16x8 a, bf16x8 b, f32x4 c) { return __builtin_amdgcn_mfma_f32_16x16x32_bf16(a, b, c, 0, 0, 0); }
; __device__ __forceinline__ void compress_task(const Params& p, int task, char* smem) {
;     ...
; #pragma unroll 2
;     for (int kq = 0; kq < 16; ++kq) {
;         const int kk = w * 16 + kq, l = kk >> 1, d = (kk & 1) * 32 + fq * 8;
;         int tok = 16 * n + l; tok = tok < S ? tok : S - 1;
;         const u32x4 raw = *(const u32x4*)(src + (size_t)tok * LDA + d);
;         const float* pp = pos + l * 64 + d;
;         const f32x4 p0 = *(const f32x4*)pp, p1 = *(const f32x4*)(pp + 4);
;         u32x4 ap;
;         ap.x = cvt_pk_bf16(bf_lo(raw.x) + p0[0], bf_hi(raw.x) + p0[1]);
;         ap.y = cvt_pk_bf16(bf_lo(raw.y) + p0[2], bf_hi(raw.y) + p0[3]);
;         ap.z = cvt_pk_bf16(bf_lo(raw.z) + p1[0], bf_hi(raw.z) + p1[1]);
;         ap.w = cvt_pk_bf16(bf_lo(raw.w) + p1[2], bf_hi(raw.w) + p1[3]);
;         const bf16x8 a = __builtin_bit_cast(bf16x8, ap);
; #pragma unroll
;         for (int nt = 0; nt < 16; ++nt) {
;             const bf16x8 bw = *(const bf16x8*)(w1t + (size_t)(nt * 16 + fr) * 2048 + kk * 32 + fq * 8);
;             acc[nt] = mfma16(bw, a, acc[nt]);
;         }
;     }
	v_mfma_f32_16x16x32_bf16 v[28:31], v[188:191], v[140:143], v[28:31]
	s_add_u32 s100, s98, 0x400
	s_addc_u32 s101, s99, 0
	global_load_dwordx4 v[188:191], v129, s[100:101]
	s_waitcnt vmcnt(15)
	v_mfma_f32_16x16x32_bf16 v[24:27], v[192:195], v[140:143], v[24:27]
	s_add_u32 s100, s98, 0x10400
	s_addc_u32 s101, s99, 0
	global_load_dwordx4 v[192:195], v129, s[100:101]
	s_waitcnt vmcnt(15)
	v_mfma_f32_16x16x32_bf16 v[20:23], v[196:199], v[106:109], v[20:23]
	s_add_u32 s100, s98, 0x20000
	s_addc_u32 s101, s99, 0
	global_load_dwordx4 v[196:199], v129, s[100:101]
	s_waitcnt vmcnt(15)
	v_mfma_f32_16x16x32_bf16 v[16:19], v[200:203], v[106:109], v[16:19]
	s_add_u32 s100, s98, 0x30000
	s_addc_u32 s101, s99, 0
	global_load_dwordx4 v[200:203], v129, s[100:101]
	s_waitcnt vmcnt(15)
	v_mfma_f32_16x16x32_bf16 v[20:23], v[204:207], v[140:143], v[20:23]
	s_add_u32 s100, s98, 0x20400
	s_addc_u32 s101, s99, 0
	global_load_dwordx4 v[204:207], v129, s[100:101]
	s_waitcnt vmcnt(15)
	v_mfma_f32_16x16x32_bf16 v[16:19], v[208:211], v[140:143], v[16:19]
	s_add_u32 s100, s98, 0x30400
	s_addc_u32 s101, s99, 0
	global_load_dwordx4 v[208:211], v129, s[100:101]
	s_waitcnt vmcnt(15)
	v_mfma_f32_16x16x32_bf16 v[12:15], v[212:215], v[106:109], v[12:15]
	s_add_u32 s100, s98, 0x40000
	s_addc_u32 s101, s99, 0
	global_load_dwordx4 v[212:215], v129, s[100:101]
	s_waitcnt vmcnt(15)
	v_mfma_f32_16x16x32_bf16 v[8:11], v[216:219], v[106:109], v[8:11]
	s_add_u32 s100, s98, 0x50000
	s_addc_u32 s101, s99, 0
	global_load_dwordx4 v[216:219], v129, s[100:101]
	s_waitcnt vmcnt(15)
	v_mfma_f32_16x16x32_bf16 v[12:15], v[220:223], v[140:143], v[12:15]
	s_add_u32 s100, s98, 0x40400
	s_addc_u32 s101, s99, 0
	global_load_dwordx4 v[220:223], v129, s[100:101]
	s_waitcnt vmcnt(15)
	v_mfma_f32_16x16x32_bf16 v[8:11], v[224:227], v[140:143], v[8:11]
	s_add_u32 s100, s98, 0x50400
	s_addc_u32 s101, s99, 0
	global_load_dwordx4 v[224:227], v129, s[100:101]
	s_waitcnt vmcnt(15)
	v_mfma_f32_16x16x32_bf16 v[4:7], v[228:231], v[106:109], v[4:7]
	s_add_u32 s100, s98, 0x60000
	s_addc_u32 s101, s99, 0
	global_load_dwordx4 v[228:231], v129, s[100:101]
	s_waitcnt vmcnt(15)
	v_mfma_f32_16x16x32_bf16 v[0:3], v[232:235], v[106:109], v[0:3]
	s_add_u32 s100, s98, 0x70000
	s_addc_u32 s101, s99, 0
	global_load_dwordx4 v[232:235], v129, s[100:101]
	s_waitcnt vmcnt(15)
	v_mfma_f32_16x16x32_bf16 v[4:7], v[236:239], v[140:143], v[4:7]
	s_add_u32 s100, s98, 0x60400
	s_addc_u32 s101, s99, 0
	global_load_dwordx4 v[236:239], v129, s[100:101]
	s_waitcnt vmcnt(15)
	v_mfma_f32_16x16x32_bf16 v[0:3], v[240:243], v[140:143], v[0:3]
	s_add_u32 s100, s98, 0x70400
	s_addc_u32 s101, s99, 0
	global_load_dwordx4 v[240:243], v129, s[100:101]
	s_add_i32 s18, s18, 1
	s_cmp_lt_u32 s18, 7
	s_cbranch_scc1 .Lcp_loop
	s_waitcnt vmcnt(16)
	v_lshlrev_b32_e32 v118, 16, v162
	v_and_b32_e32 v119, 0xffff0000, v162
	v_lshlrev_b32_e32 v120, 16, v163
	v_and_b32_e32 v121, 0xffff0000, v163
	v_lshlrev_b32_e32 v122, 16, v164
	v_and_b32_e32 v123, 0xffff0000, v164
	v_lshlrev_b32_e32 v124, 16, v165
	v_and_b32_e32 v125, 0xffff0000, v165
	v_pk_add_f32 v[118:119], v[166:167], v[118:119]
	v_pk_add_f32 v[120:121], v[168:169], v[120:121]
	v_pk_add_f32 v[122:123], v[170:171], v[122:123]
	v_pk_add_f32 v[124:125], v[172:173], v[124:125]
	v_cvt_pk_bf16_f32 v106, v118, v119
	v_cvt_pk_bf16_f32 v107, v120, v121
	v_cvt_pk_bf16_f32 v108, v122, v123
	v_cvt_pk_bf16_f32 v109, v124, v125
	v_lshlrev_b32_e32 v118, 16, v174
	v_and_b32_e32 v119, 0xffff0000, v174
	v_lshlrev_b32_e32 v120, 16, v175
	v_and_b32_e32 v121, 0xffff0000, v175
	v_lshlrev_b32_e32 v122, 16, v176
	v_and_b32_e32 v123, 0xffff0000, v176
	v_lshlrev_b32_e32 v124, 16, v177
	v_and_b32_e32 v125, 0xffff0000, v177
	v_pk_add_f32 v[118:119], v[246:247], v[118:119]
	v_pk_add_f32 v[120:121], v[248:249], v[120:121]
	v_pk_add_f32 v[122:123], v[250:251], v[122:123]
	v_pk_add_f32 v[124:125], v[252:253], v[124:125]
	v_cvt_pk_bf16_f32 v140, v118, v119
	v_cvt_pk_bf16_f32 v141, v120, v121
	v_cvt_pk_bf16_f32 v142, v122, v123
	v_cvt_pk_bf16_f32 v143, v124, v125
	s_waitcnt vmcnt(15)
	v_mfma_f32_16x16x32_bf16 v[60:63], v[180:183], v[106:109], v[60:63]
	s_add_u32 s100, s98, 0x80000
	s_addc_u32 s101, s99, 0
	global_load_dwordx4 v[180:183], v129, s[100:101]
	s_waitcnt vmcnt(15)
	v_mfma_f32_16x16x32_bf16 v[56:59], v[184:187], v[106:109], v[56:59]
	s_add_u32 s100, s98, 0x90000
	s_addc_u32 s101, s99, 0
	global_load_dwordx4 v[184:187], v129, s[100:101]
	s_waitcnt vmcnt(15)
	v_mfma_f32_16x16x32_bf16 v[60:63], v[188:191], v[140:143], v[60:63]
	s_add_u32 s100, s98, 0x80400
	s_addc_u32 s101, s99, 0
	global_load_dwordx4 v[188:191], v129, s[100:101]
	s_waitcnt vmcnt(15)
	v_mfma_f32_16x16x32_bf16 v[56:59], v[192:195], v[140:143], v[56:59]
	s_add_u32 s100, s98, 0x90400
	s_addc_u32 s101, s99, 0
	global_load_dwordx4 v[192:195], v129, s[100:101]
	s_waitcnt vmcnt(15)
; __device__ __forceinline__ f32x4 mfma16(bf16x8 a, bf16x8 b, f32x4 c) { return __builtin_amdgcn_mfma_f32_16x16x32_bf16(a, b, c, 0, 0, 0); }
; __device__ __forceinline__ void compress_task(const Params& p, int task, char* smem) {
;     ...
;         for (int nt = 0; nt < 16; ++nt) {
;             const bf16x8 bw = *(const bf16x8*)(w1t + (size_t)(nt * 16 + fr) * 2048 + kk * 32 + fq * 8);
;             acc[nt] = mfma16(bw, a, acc[nt]);
;         }
;     }
;     float* red = (float*)smem;
;     bf16_t* hid = (bf16_t*)(smem + 49920);
;     if (w > 0) {
; #pragma unroll
;         for (int nt = 0; nt < 16; ++nt) *(f32x4*)(red + ((w - 1) * 16 + fr) * 260 + nt * 16 + fq * 4) = acc[nt];
;     ...
;         const bf16x8 wf = *(const bf16x8*)(w2t + (size_t)(w * 16 + fr) * 256 + kk * 32 + fq * 8);
	v_mfma_f32_16x16x32_bf16 v[52:55], v[196:199], v[106:109], v[52:55]
	s_add_u32 s100, s98, 0xa0000
	s_addc_u32 s101, s99, 0
	global_load_dwordx4 v[196:199], v129, s[100:101]
	s_waitcnt vmcnt(15)
	v_mfma_f32_16x16x32_bf16 v[48:51], v[200:203], v[106:109], v[48:51]
	s_add_u32 s100, s98, 0xb0000
	s_addc_u32 s101, s99, 0
	global_load_dwordx4 v[200:203], v129, s[100:101]
	s_waitcnt vmcnt(15)
	v_mfma_f32_16x16x32_bf16 v[52:55], v[204:207], v[140:143], v[52:55]
	s_add_u32 s100, s98, 0xa0400
	s_addc_u32 s101, s99, 0
	global_load_dwordx4 v[204:207], v129, s[100:101]
	s_waitcnt vmcnt(15)
	v_mfma_f32_16x16x32_bf16 v[48:51], v[208:211], v[140:143], v[48:51]
	s_add_u32 s100, s98, 0xb0400
	s_addc_u32 s101, s99, 0
	global_load_dwordx4 v[208:211], v129, s[100:101]
	s_waitcnt vmcnt(15)
	v_mfma_f32_16x16x32_bf16 v[44:47], v[212:215], v[106:109], v[44:47]
	s_add_u32 s100, s98, 0xc0000
	s_addc_u32 s101, s99, 0
	global_load_dwordx4 v[212:215], v129, s[100:101]
	s_waitcnt vmcnt(15)
	v_mfma_f32_16x16x32_bf16 v[40:43], v[216:219], v[106:109], v[40:43]
	s_add_u32 s100, s98, 0xd0000
	s_addc_u32 s101, s99, 0
	global_load_dwordx4 v[216:219], v129, s[100:101]
	s_waitcnt vmcnt(15)
	v_mfma_f32_16x16x32_bf16 v[44:47], v[220:223], v[140:143], v[44:47]
	s_add_u32 s100, s98, 0xc0400
	s_addc_u32 s101, s99, 0
	global_load_dwordx4 v[220:223], v129, s[100:101]
	s_waitcnt vmcnt(15)
	v_mfma_f32_16x16x32_bf16 v[40:43], v[224:227], v[140:143], v[40:43]
	s_add_u32 s100, s98, 0xd0400
	s_addc_u32 s101, s99, 0
	global_load_dwordx4 v[224:227], v129, s[100:101]
	s_waitcnt vmcnt(15)
	v_mfma_f32_16x16x32_bf16 v[36:39], v[228:231], v[106:109], v[36:39]
	s_add_u32 s100, s98, 0xe0000
	s_addc_u32 s101, s99, 0
	global_load_dwordx4 v[228:231], v129, s[100:101]
	s_waitcnt vmcnt(15)
	v_mfma_f32_16x16x32_bf16 v[32:35], v[232:235], v[106:109], v[32:35]
	s_add_u32 s100, s98, 0xf0000
	s_addc_u32 s101, s99, 0
	global_load_dwordx4 v[232:235], v129, s[100:101]
	s_waitcnt vmcnt(15)
	v_mfma_f32_16x16x32_bf16 v[36:39], v[236:239], v[140:143], v[36:39]
	s_add_u32 s100, s98, 0xe0400
	s_addc_u32 s101, s99, 0
	global_load_dwordx4 v[236:239], v129, s[100:101]
	s_waitcnt vmcnt(15)
	v_mfma_f32_16x16x32_bf16 v[32:35], v[240:243], v[140:143], v[32:35]
	s_add_u32 s100, s98, 0xf0400
	s_addc_u32 s101, s99, 0
	global_load_dwordx4 v[240:243], v129, s[100:101]
	s_waitcnt vmcnt(15)
	v_mfma_f32_16x16x32_bf16 v[28:31], v[180:183], v[106:109], v[28:31]
	s_waitcnt vmcnt(14)
	v_mfma_f32_16x16x32_bf16 v[24:27], v[184:187], v[106:109], v[24:27]
	s_waitcnt vmcnt(13)
	v_mfma_f32_16x16x32_bf16 v[28:31], v[188:191], v[140:143], v[28:31]
	s_waitcnt vmcnt(12)
	v_mfma_f32_16x16x32_bf16 v[24:27], v[192:195], v[140:143], v[24:27]
	s_waitcnt vmcnt(11)
	v_mfma_f32_16x16x32_bf16 v[20:23], v[196:199], v[106:109], v[20:23]
	s_waitcnt vmcnt(10)
	v_mfma_f32_16x16x32_bf16 v[16:19], v[200:203], v[106:109], v[16:19]
	s_waitcnt vmcnt(9)
	v_mfma_f32_16x16x32_bf16 v[20:23], v[204:207], v[140:143], v[20:23]
	s_waitcnt vmcnt(8)
	v_mfma_f32_16x16x32_bf16 v[16:19], v[208:211], v[140:143], v[16:19]
	s_waitcnt vmcnt(7)
	v_mfma_f32_16x16x32_bf16 v[12:15], v[212:215], v[106:109], v[12:15]
	s_waitcnt vmcnt(6)
	v_mfma_f32_16x16x32_bf16 v[8:11], v[216:219], v[106:109], v[8:11]
	s_waitcnt vmcnt(5)
	v_mfma_f32_16x16x32_bf16 v[12:15], v[220:223], v[140:143], v[12:15]
	s_waitcnt vmcnt(4)
	v_mfma_f32_16x16x32_bf16 v[8:11], v[224:227], v[140:143], v[8:11]
	s_waitcnt vmcnt(3)
	v_mfma_f32_16x16x32_bf16 v[4:7], v[228:231], v[106:109], v[4:7]
	s_waitcnt vmcnt(2)
	v_mfma_f32_16x16x32_bf16 v[0:3], v[232:235], v[106:109], v[0:3]
	s_waitcnt vmcnt(1)
	v_mfma_f32_16x16x32_bf16 v[4:7], v[236:239], v[140:143], v[4:7]
	s_waitcnt vmcnt(0)
	v_mfma_f32_16x16x32_bf16 v[0:3], v[240:243], v[140:143], v[0:3]
	s_cmpk_lt_u32 s42, 0x200
	s_cselect_b32 s100, s39, 0x3148000
	s_mov_b32 s101, 0
	v_lshl_add_u64 v[126:127], v[68:69], 0, s[100:101]
	global_load_dwordx4 v[180:183], v[126:127], off
	global_load_dwordx4 v[184:187], v[126:127], off offset:64
	global_load_dwordx4 v[188:191], v[126:127], off offset:128
	global_load_dwordx4 v[192:195], v[126:127], off offset:192
	global_load_dwordx4 v[196:199], v[126:127], off offset:256
	global_load_dwordx4 v[200:203], v[126:127], off offset:320
	global_load_dwordx4 v[204:207], v[126:127], off offset:384
	global_load_dwordx4 v[208:211], v[126:127], off offset:448
	s_and_saveexec_b64 s[18:19], s[6:7]
	s_cbranch_execz .LBB0_253
	ds_write_b128 v99, v[60:63]
	ds_write_b128 v99, v[56:59] offset:64
	ds_write_b128 v99, v[52:55] offset:128
	ds_write_b128 v99, v[48:51] offset:192
	ds_write_b128 v99, v[44:47] offset:256
	ds_write_b128 v99, v[40:43] offset:320
	ds_write_b128 v99, v[36:39] offset:384
	ds_write_b128 v99, v[32:35] offset:448
	ds_write_b128 v99, v[28:31] offset:512
	ds_write_b128 v99, v[24:27] offset:576
	ds_write_b128 v99, v[20:23] offset:640
	ds_write_b128 v99, v[16:19] offset:704
	ds_write_b128 v99, v[12:15] offset:768
	ds_write_b128 v99, v[8:11] offset:832
	ds_write_b128 v99, v[4:7] offset:896
	ds_write_b128 v99, v[0:3] offset:960

; __device__ __forceinline__ f32x4 mfma16(bf16x8 a, bf16x8 b, f32x4 c) { return __builtin_amdgcn_mfma_f32_16x16x32_bf16(a, b, c, 0, 0, 0); }
; __device__ __forceinline__ f32x4 zero4() { return (f32x4){0.f, 0.f, 0.f, 0.f}; }
; __device__ __forceinline__ void compress_task(const Params& p, int task, char* smem) {
;     ...
;     __syncthreads();
;     f32x4 o = zero4();
; #pragma unroll
;     for (int kk = 0; kk < 8; ++kk) {
;         const bf16x8 hf = *(const bf16x8*)(hid + fr * 264 + kk * 32 + fq * 8);
;         const bf16x8 wf = *(const bf16x8*)(w2t + (size_t)(w * 16 + fr) * 256 + kk * 32 + fq * 8);
;         if (kv == 0) o = mfma16(wf, hf, o);
;         else o = mfma16(hf, wf, o);
;     }
.LBB0_255:
	s_or_b64 exec, exec, s[18:19]
	s_and_b64 s[0:1], s[0:1], exec
	s_cselect_b32 s10, s39, 0x3148000
	v_lshl_add_u64 v[16:17], v[68:69], 0, s[10:11]
	s_waitcnt lgkmcnt(0)
	s_barrier
	s_waitcnt vmcnt(0)
	v_mov_b32_e32 v4, v180
	v_mov_b32_e32 v5, v181
	v_mov_b32_e32 v6, v182
	v_mov_b32_e32 v7, v183
	s_nop 1
	v_add_u32_e32 v18, v66, v85
	ds_read_b128 v[8:11], v18 offset:49920
	s_mov_b64 s[0:1], -1
	s_and_b64 vcc, exec, s[16:17]
	s_cbranch_vccz .LBB0_257
	s_mov_b64 s[0:1], 0
	s_waitcnt vmcnt(0) lgkmcnt(0)
	v_mfma_f32_16x16x32_bf16 v[0:3], v[8:11], v[4:7], 0

; __device__ __forceinline__ f32x4 mfma16(bf16x8 a, bf16x8 b, f32x4 c) { return __builtin_amdgcn_mfma_f32_16x16x32_bf16(a, b, c, 0, 0, 0); }
; __device__ __forceinline__ void compress_task(const Params& p, int task, char* smem) {
;     ...
;     for (int kk = 0; kk < 8; ++kk) {
;         const bf16x8 hf = *(const bf16x8*)(hid + fr * 264 + kk * 32 + fq * 8);
;         const bf16x8 wf = *(const bf16x8*)(w2t + (size_t)(w * 16 + fr) * 256 + kk * 32 + fq * 8);
;         if (kv == 0) o = mfma16(wf, hf, o);
;         else o = mfma16(hf, wf, o);
;     }
.LBB0_259:
	s_waitcnt lgkmcnt(0)
	v_mov_b32_e32 v8, v184
	v_mov_b32_e32 v9, v185
	v_mov_b32_e32 v10, v186
	v_mov_b32_e32 v11, v187
	s_nop 1
	ds_read_b128 v[12:15], v18 offset:49984
	s_waitcnt vmcnt(1)
	v_cndmask_b32_e64 v4, 0, 1, s[16:17]
	v_cmp_ne_u32_e64 s[0:1], 1, v4
	s_andn2_b64 vcc, exec, s[16:17]
	s_mov_b64 s[18:19], -1
	s_cbranch_vccnz .LBB0_261
	s_waitcnt vmcnt(0) lgkmcnt(0)
	v_mfma_f32_16x16x32_bf16 v[4:7], v[12:15], v[8:11], v[0:3]
	s_mov_b64 s[18:19], 0

; __device__ __forceinline__ f32x4 mfma16(bf16x8 a, bf16x8 b, f32x4 c) { return __builtin_amdgcn_mfma_f32_16x16x32_bf16(a, b, c, 0, 0, 0); }
; __device__ __forceinline__ void compress_task(const Params& p, int task, char* smem) {
;     ...
;     for (int kk = 0; kk < 8; ++kk) {
;         const bf16x8 hf = *(const bf16x8*)(hid + fr * 264 + kk * 32 + fq * 8);
;         const bf16x8 wf = *(const bf16x8*)(w2t + (size_t)(w * 16 + fr) * 256 + kk * 32 + fq * 8);
;         if (kv == 0) o = mfma16(wf, hf, o);
;         else o = mfma16(hf, wf, o);
;     }
.LBB0_263:
	v_mov_b32_e32 v8, v188
	v_mov_b32_e32 v9, v189
	v_mov_b32_e32 v10, v190
	v_mov_b32_e32 v11, v191
	s_nop 1
	s_waitcnt lgkmcnt(0)
	ds_read_b128 v[12:15], v18 offset:50048
	s_and_b64 vcc, exec, s[0:1]
	s_mov_b64 s[18:19], -1
	s_cbranch_vccnz .LBB0_265
	s_waitcnt vmcnt(0) lgkmcnt(0)
	v_mfma_f32_16x16x32_bf16 v[0:3], v[12:15], v[8:11], v[4:7]
	s_mov_b64 s[18:19], 0

; __device__ __forceinline__ f32x4 mfma16(bf16x8 a, bf16x8 b, f32x4 c) { return __builtin_amdgcn_mfma_f32_16x16x32_bf16(a, b, c, 0, 0, 0); }
; __device__ __forceinline__ void compress_task(const Params& p, int task, char* smem) {
;     ...
;     for (int kk = 0; kk < 8; ++kk) {
;         const bf16x8 hf = *(const bf16x8*)(hid + fr * 264 + kk * 32 + fq * 8);
;         const bf16x8 wf = *(const bf16x8*)(w2t + (size_t)(w * 16 + fr) * 256 + kk * 32 + fq * 8);
;         if (kv == 0) o = mfma16(wf, hf, o);
;         else o = mfma16(hf, wf, o);
;     }
.LBB0_267:
	v_mov_b32_e32 v8, v192
	v_mov_b32_e32 v9, v193
	v_mov_b32_e32 v10, v194
	v_mov_b32_e32 v11, v195
	s_nop 1
	s_waitcnt lgkmcnt(0)
	ds_read_b128 v[12:15], v18 offset:50112
	s_and_b64 vcc, exec, s[0:1]
	s_mov_b64 s[18:19], -1
	s_cbranch_vccnz .LBB0_269
	s_waitcnt vmcnt(0) lgkmcnt(0)
	v_mfma_f32_16x16x32_bf16 v[4:7], v[12:15], v[8:11], v[0:3]
	s_mov_b64 s[18:19], 0

; __device__ __forceinline__ f32x4 mfma16(bf16x8 a, bf16x8 b, f32x4 c) { return __builtin_amdgcn_mfma_f32_16x16x32_bf16(a, b, c, 0, 0, 0); }
; __device__ __forceinline__ void compress_task(const Params& p, int task, char* smem) {
;     ...
;     for (int kk = 0; kk < 8; ++kk) {
;         const bf16x8 hf = *(const bf16x8*)(hid + fr * 264 + kk * 32 + fq * 8);
;         const bf16x8 wf = *(const bf16x8*)(w2t + (size_t)(w * 16 + fr) * 256 + kk * 32 + fq * 8);
;         if (kv == 0) o = mfma16(wf, hf, o);
;         else o = mfma16(hf, wf, o);
;     }
.LBB0_271:
	v_mov_b32_e32 v8, v196
	v_mov_b32_e32 v9, v197
	v_mov_b32_e32 v10, v198
	v_mov_b32_e32 v11, v199
	s_nop 1
	s_waitcnt lgkmcnt(0)
	ds_read_b128 v[12:15], v18 offset:50176
	s_and_b64 vcc, exec, s[0:1]
	s_mov_b64 s[18:19], -1
	s_cbranch_vccnz .LBB0_273
	s_waitcnt vmcnt(0) lgkmcnt(0)
	v_mfma_f32_16x16x32_bf16 v[0:3], v[12:15], v[8:11], v[4:7]
	s_mov_b64 s[18:19], 0

; __device__ __forceinline__ f32x4 mfma16(bf16x8 a, bf16x8 b, f32x4 c) { return __builtin_amdgcn_mfma_f32_16x16x32_bf16(a, b, c, 0, 0, 0); }
; __device__ __forceinline__ void compress_task(const Params& p, int task, char* smem) {
;     ...
;     for (int kk = 0; kk < 8; ++kk) {
;         const bf16x8 hf = *(const bf16x8*)(hid + fr * 264 + kk * 32 + fq * 8);
;         const bf16x8 wf = *(const bf16x8*)(w2t + (size_t)(w * 16 + fr) * 256 + kk * 32 + fq * 8);
;         if (kv == 0) o = mfma16(wf, hf, o);
;         else o = mfma16(hf, wf, o);
;     }
.LBB0_275:
	v_mov_b32_e32 v8, v200
	v_mov_b32_e32 v9, v201
	v_mov_b32_e32 v10, v202
	v_mov_b32_e32 v11, v203
	s_nop 1
	s_waitcnt lgkmcnt(0)
	ds_read_b128 v[12:15], v18 offset:50240
	s_and_b64 vcc, exec, s[0:1]
	s_mov_b64 s[18:19], -1
	s_cbranch_vccnz .LBB0_277
	s_waitcnt vmcnt(0) lgkmcnt(0)
	v_mfma_f32_16x16x32_bf16 v[4:7], v[12:15], v[8:11], v[0:3]
	s_mov_b64 s[18:19], 0

; __device__ __forceinline__ f32x4 mfma16(bf16x8 a, bf16x8 b, f32x4 c) { return __builtin_amdgcn_mfma_f32_16x16x32_bf16(a, b, c, 0, 0, 0); }
; __device__ __forceinline__ void compress_task(const Params& p, int task, char* smem) {
;     ...
;     for (int kk = 0; kk < 8; ++kk) {
;         const bf16x8 hf = *(const bf16x8*)(hid + fr * 264 + kk * 32 + fq * 8);
;         const bf16x8 wf = *(const bf16x8*)(w2t + (size_t)(w * 16 + fr) * 256 + kk * 32 + fq * 8);
;         if (kv == 0) o = mfma16(wf, hf, o);
;         else o = mfma16(hf, wf, o);
;     }
.LBB0_279:
	s_nop 2
	v_mov_b32_e32 v0, v204
	v_mov_b32_e32 v1, v205
	v_mov_b32_e32 v2, v206
	v_mov_b32_e32 v3, v207
	s_nop 1
	s_waitcnt lgkmcnt(0)
	ds_read_b128 v[12:15], v18 offset:50304
	s_and_b64 vcc, exec, s[0:1]
	s_mov_b64 s[18:19], -1
	s_cbranch_vccnz .LBB0_281
	s_waitcnt vmcnt(0) lgkmcnt(0)
	v_mfma_f32_16x16x32_bf16 v[8:11], v[12:15], v[0:3], v[4:7]
	s_mov_b64 s[18:19], 0

; __device__ __forceinline__ f32x4 mfma16(bf16x8 a, bf16x8 b, f32x4 c) { return __builtin_amdgcn_mfma_f32_16x16x32_bf16(a, b, c, 0, 0, 0); }
; __device__ __forceinline__ void compress_task(const Params& p, int task, char* smem) {
;     ...
;     for (int kk = 0; kk < 8; ++kk) {
;         const bf16x8 hf = *(const bf16x8*)(hid + fr * 264 + kk * 32 + fq * 8);
;         const bf16x8 wf = *(const bf16x8*)(w2t + (size_t)(w * 16 + fr) * 256 + kk * 32 + fq * 8);
;         if (kv == 0) o = mfma16(wf, hf, o);
;         else o = mfma16(hf, wf, o);
;     }
.LBB0_283:
	s_nop 2
	v_mov_b32_e32 v4, v208
	v_mov_b32_e32 v5, v209
	v_mov_b32_e32 v6, v210
	v_mov_b32_e32 v7, v211
	s_nop 1
	s_waitcnt lgkmcnt(0)
	ds_read_b128 v[12:15], v18 offset:50368
	s_and_b64 vcc, exec, s[0:1]
	s_mov_b64 s[0:1], -1
	s_cbranch_vccnz .LBB0_285
	s_waitcnt vmcnt(0) lgkmcnt(0)
	v_mfma_f32_16x16x32_bf16 v[0:3], v[12:15], v[4:7], v[8:11]
	s_mov_b64 s[0:1], 0
